# v57 + static first P0 item per workgroup (item = blockIdx; counter tickets offset by 256)
# speedup vs baseline: 1.0004x; 1.0004x over previous
; #define LAS __attribute__((address_space(3)))
; __device__ __forceinline__ int opaque_tid() { int t; asm volatile("v_mov_b32 %0, %1" : "=v"(t) : "v"((int)threadIdx.x)); return t; }
; __device__ __forceinline__ unsigned f2bf(float f) { unsigned u = __builtin_bit_cast(unsigned, f); return (u + 0x7fffu + ((u >> 16) & 1u)) >> 16; }
; #define ws (opq(P.ws))
; __global__ void __launch_bounds__(NTHREADS, 2) mega_fwd(Params P) {
;     ...
;         const int tid = opaque_tid(), lane = tid & 63, wid = __builtin_amdgcn_readfirstlane(tid >> 6);
;         const int gw = bx * NWAVES + wid, NGW = G * NWAVES;
;         LAS float* scv = (LAS float*)(ldsl + 69632);
;         LAS float* red = (LAS float*)(ldsl + 69632 + 12288);
;         for (int i = tid; i < 3 * DM; i += NTHREADS) { const int v = i / DM, k = i % DM; const float cv = (v < 2) ? P.c[v * DM + k] : P.c_ctx[k]; scv[i] = cv / (1.0f + __expf(-cv)); }
;         __syncthreads();
;         if (bx == 0 && wid == 0) { for (int l2 = 0; l2 < DEPTH; ++l2) { float a = fabsf(P.g_q[l2 * 64 + lane]), c2 = fabsf(P.g_k[l2 * 64 + lane]);
; #pragma unroll
;                 for (int o_ = 1; o_ < 64; o_ <<= 1) { a = fmaxf(a, __shfl_xor(a, o_)); c2 = fmaxf(c2, __shfl_xor(c2, o_)); }
;                 if (lane == 0) tcos[4096 + l2] = fminf(8.0f * LOG2E * 1.02f * a * c2, 60.0f); } }
;         for (int i = bx * NTHREADS + tid; i < 128 * 16; i += G * NTHREADS) { const int pos = i >> 4, f = i & 15;
;             const float inv = exp2f(-(float)f * (13.287712379549449f / 16.0f)); const float ang = (float)pos * inv;
;             tcos[i] = cosf(ang); tsin[i] = sinf(ang); }
;         { bf16_t* Wsb = (bf16_t*)(ws + WS_WS); for (int i = bx * NTHREADS + tid; i < DEPTH * 4 * 128 * 128; i += G * NTHREADS) Wsb[i] = (bf16_t)f2bf(P.w_s[i]); }
;         LAS float* scr = (LAS float*)(ldsl + wid * 8448);
;         LAS int* qslot = (LAS int*)(ldsl + RING_BYTES + 1024);
;         for (;;) {
;             if (tid == 0) qslot[0] = (int)atomicAdd(ctl + 64 * 20, 1u);
;             __syncthreads();
;             const int qi = __builtin_amdgcn_readfirstlane(qslot[0]);
;             __syncthreads();
;             if (qi >= DEPTH * 24 + CV_L / 8) break;
.LBB0_40:
	s_or_b64 exec, exec, s[4:5]
	s_ashr_i32 s0, s20, 6
	s_mul_i32 s1, s0, 0x2100
	s_add_i32 s1, s1, 0
	s_add_i32 s16, s0, 0xfffffd00
	s_add_u32 s12, s76, 0x1600000
	s_addc_u32 s13, s77, 0
	s_add_u32 s14, s76, 0x1e00000
	s_addc_u32 s15, s77, 0
	s_add_u32 s18, s76, 0x4a00000
	s_addc_u32 s19, s77, 0
	v_readlane_b32 s4, v253, 0
	v_readlane_b32 s5, v253, 1
	v_readlane_b32 s6, v253, 2
	v_readlane_b32 s7, v253, 3
	v_readlane_b32 s8, v253, 4
	v_readlane_b32 s9, v253, 5
	v_readlane_b32 s10, v253, 6
	v_readlane_b32 s11, v253, 7
	v_writelane_b32 v253, s18, 41
	v_lshlrev_b32_e32 v2, 3, v8
	v_lshlrev_b32_e32 v4, 4, v8
	v_writelane_b32 v253, s19, 42
	v_writelane_b32 v253, s14, 43
	v_mov_b32_e32 v41, 0
	v_and_b32_e32 v2, 56, v2
	v_writelane_b32 v253, s15, 44
	v_lshrrev_b32_e32 v39, 3, v8
	v_readlane_b32 s40, v253, 25
	v_readlane_b32 s44, v253, 29
	v_readlane_b32 s45, v253, 30
	v_readlane_b32 s46, v253, 31
	v_readlane_b32 s47, v253, 32
	v_readlane_b32 s48, v253, 33
	v_readlane_b32 s49, v253, 34
	v_readlane_b32 s50, v253, 35
	v_readlane_b32 s51, v253, 36
	v_readlane_b32 s52, v253, 37
	v_readlane_b32 s53, v253, 38
	v_readlane_b32 s54, v253, 39
	v_readlane_b32 s55, v253, 40
	s_mov_b64 s[20:21], s[44:45]
	s_mov_b64 s[26:27], s[50:51]
	s_cmp_lg_u64 s[26:27], 0
	s_cselect_b64 s[4:5], -1, 0
	v_readlane_b32 s41, v253, 26
	v_readlane_b32 s42, v253, 27
	v_readlane_b32 s43, v253, 28
	v_writelane_b32 v253, s4, 45
	s_mov_b64 s[22:23], s[46:47]
	s_mov_b64 s[24:25], s[48:49]
	v_writelane_b32 v253, s5, 46
	v_writelane_b32 v253, s12, 47
	s_add_u32 s4, s76, 0x400000
	s_mov_b64 s[28:29], s[52:53]
	v_writelane_b32 v253, s13, 48
	s_mov_b64 s[30:31], s[54:55]
	s_addc_u32 s5, s77, 0
	v_readlane_b32 s40, v253, 9
	v_and_b32_e32 v40, 0x70, v4
	v_mul_u32_u24_e32 v7, 0x84, v2
	v_lshlrev_b32_e32 v2, 1, v2
	s_waitcnt lgkmcnt(0)
	v_mov_b32_e32 v3, v41
	v_readlane_b32 s41, v253, 10
	v_readlane_b32 s42, v253, 11
	v_readlane_b32 s43, v253, 12
	v_readlane_b32 s44, v253, 13
	v_readlane_b32 s45, v253, 14
	v_readlane_b32 s46, v253, 15
	v_readlane_b32 s47, v253, 16
	v_readlane_b32 s48, v253, 17
	v_readlane_b32 s49, v253, 18
	v_readlane_b32 s50, v253, 19
	v_readlane_b32 s51, v253, 20
	v_readlane_b32 s52, v253, 21
	v_readlane_b32 s53, v253, 22
	v_readlane_b32 s54, v253, 23
	v_readlane_b32 s55, v253, 24
	v_writelane_b32 v253, s4, 49
	v_lshlrev_b32_e32 v8, 2, v39
	v_lshl_add_u64 v[46:47], s[6:7], 0, v[40:41]
	v_writelane_b32 v253, s5, 50
	v_lshl_add_u64 v[56:57], s[4:5], 0, v[2:3]
	s_mul_i32 s4, s0, 0xc00
	s_add_i32 s33, 0, 0x14000
	s_lshl_b32 s6, s0, 9
	v_add_u32_e32 v5, s1, v40
	v_lshl_add_u64 v[44:45], s[18:19], 0, v[2:3]
	v_add3_u32 v68, s1, v7, v8
	s_lshl_b32 s1, s0, 7
	s_add_i32 s4, s33, s4
	s_add_i32 s18, s6, 0
	s_mul_i32 s0, s0, 0x300000
	s_mul_hi_i32 s1, s1, 0x6000
	s_add_u32 s0, s48, s0
	s_addc_u32 s1, s49, s1
	v_mul_u32_u24_e32 v6, 0x84, v39
	v_or_b32_e32 v7, 32, v39
	s_add_u32 s20, s0, 0x2a000
	v_mul_u32_u24_e32 v7, 0x84, v7
	v_add_u32_e32 v69, s4, v4
	s_movk_i32 s4, 0x300
	v_and_b32_e32 v58, 0xff, v1
	s_addc_u32 s21, s1, 0
	s_add_i32 s22, 0, 0x20400
	v_add_u32_e32 v73, v5, v6
	v_lshl_add_u64 v[42:43], s[8:9], 0, v[40:41]
	v_or_b32_e32 v59, 8, v39
	v_or_b32_e32 v66, 16, v39
	v_or_b32_e32 v67, 24, v39
	v_lshl_add_u64 v[48:49], s[14:15], 0, v[2:3]
	v_lshl_add_u64 v[50:51], s[28:29], 0, v[40:41]
	v_lshl_add_u64 v[52:53], s[12:13], 0, v[2:3]
	v_lshl_add_u64 v[54:55], s[52:53], 0, v[40:41]
	v_cmp_gt_i32_e64 s[4:5], s4, v1
	s_movk_i32 s17, 0xff
	v_lshl_add_u32 v70, v58, 2, s33
	s_movk_i32 s19, 0x6000
	v_mov_b32_e32 v71, 1
	v_add_u32_e32 v74, 0x420, v73
	v_add_u32_e32 v75, 0x428, v73
	v_add_u32_e32 v76, 0x840, v73
	v_add_u32_e32 v77, 0x848, v73
	v_add_u32_e32 v78, 0xc60, v73
	v_add_u32_e32 v79, 0xc68, v73
	v_add_u32_e32 v80, 0x1080, v73
	v_add_u32_e32 v81, 0x1088, v73
	v_add_u32_e32 v82, 0x14a0, v73
	v_add_u32_e32 v83, 0x14a8, v73
	v_add_u32_e32 v84, 0x18c0, v73
	v_add_u32_e32 v85, 0x18c8, v73
	v_add_u32_e32 v86, 0x1ce0, v73
	v_add_u32_e32 v87, 0x1ce8, v73
	s_movk_i32 s23, 0x7fff
	s_mov_b32 s24, 0xffff0000
	s_mov_b32 s25, 0x2c000
	s_mov_b32 s26, 0x58000
	s_mov_b32 s27, 0x84000
	s_mov_b32 s28, 0xb0000
	s_mov_b32 s29, 0xdc000
	s_mov_b32 s30, 0x108000
	v_mov_b32_e32 v88, s22
	v_add_u32_e32 v89, v5, v7
	s_mov_b32 s31, 0x134000
	s_movk_i32 s34, 0x2400
	s_mov_b32 s35, 0xfffdc000
	s_mov_b32 s37, 0xfffe2000
	s_mov_b32 s38, 0xfffe8000
	s_mov_b32 s39, 0xfffee000
	s_mov_b32 s40, 0xffff4000
	s_movk_i32 s41, 0xa000
	s_mov_b32 s11, 0
	v_cmp_eq_u32_e64 s[6:7], 0, v1
	s_mov_b64 s[12:13], 0x30000
	s_mov_b32 s101, 1
	s_branch .LBB0_44

; __global__ void __launch_bounds__(NTHREADS, 2) mega_fwd(Params P) {
;     ...
;         for (;;) {
;             if (tid == 0) qslot[0] = (int)atomicAdd(ctl + 64 * 20, 1u);
;             __syncthreads();
;             const int qi = __builtin_amdgcn_readfirstlane(qslot[0]);
;             __syncthreads();
;             if (qi >= DEPTH * 24 + CV_L / 8) break;
;             if (qi < DEPTH * 24) {
.LBB0_44:
	s_and_saveexec_b64 s[0:1], s[6:7]
	s_cbranch_execz .LBB0_46
	s_cmp_lg_u32 s101, 0
	s_cbranch_scc0 .Lp0_dyn
	v_mov_b32_e32 v2, s70
	v_add_u32_e32 v2, 0xffffff00, v2
	v_mov_b32_e32 v3, s22
	s_branch .Lp0_have
.Lp0_dyn:
	s_mov_b64 s[8:9], s[76:77]
	s_nop 0
	v_mov_b32_e32 v2, s8
	v_add_co_u32_e32 v2, vcc, 0x1000, v2
	v_mov_b32_e32 v3, s9
	s_nop 0
	v_addc_co_u32_e32 v3, vcc, 0, v3, vcc
	flat_atomic_add v2, v[2:3], v71 offset:1024 sc0
	v_mov_b32_e32 v3, s22
	s_waitcnt vmcnt(0) lgkmcnt(0)
.Lp0_have:
	v_add_u32_e32 v2, 0x100, v2
	ds_write_b32 v3, v2
.LBB0_46:
	s_or_b64 exec, exec, s[0:1]
	s_mov_b32 s101, 0
	s_waitcnt lgkmcnt(0)
	s_barrier
	ds_read_b32 v2, v88
	s_mov_b64 s[0:1], -1
	s_waitcnt lgkmcnt(0)
	s_barrier
	v_readfirstlane_b32 s14, v2
	s_cmpk_gt_i32 s14, 0x33f
	s_cbranch_scc1 .LBB0_43
	s_cmpk_gt_i32 s14, 0x5f
	s_cbranch_scc0 .LBB0_89
	s_lshl_b32 s0, s14, 3
	s_add_i32 s15, s16, s0
	s_cmpk_gt_i32 s15, 0x47f
	s_mov_b64 s[0:1], -1
	s_cbranch_scc0 .LBB0_70
	s_cmpk_gt_u32 s15, 0x67f
	s_cbranch_scc0 .LBB0_55
	s_cmpk_gt_u32 s15, 0x117f
	s_cbranch_scc0 .LBB0_52
; #define LAS __attribute__((address_space(3)))
; __device__ __forceinline__ unsigned pk2(float lo, float hi) { return f2bf(lo) | (f2bf(hi) << 16); }
; __device__ __forceinline__ void transpose_item(const float* W, int N, int srccol, const float* kscale, bf16_t* WT, int K, int dstrow, int k0, LAS float* scr, int lane) {
;     f32x4 t[8];
; #pragma unroll
;     for (int i = 0; i < 8; ++i) t[i] = __builtin_nontemporal_load((const f32x4*)(W + (size_t)(k0 + 8 * i + (lane >> 3)) * N + srccol + 4 * (lane & 7)));
; #pragma unroll
;     for (int i = 0; i < 8; ++i) { const int kk = 8 * i + (lane >> 3); f32x4 v = t[i]; if (kscale) v = v * kscale[k0 + kk];
;         LAS float* d = scr + kk * 33 + 4 * (lane & 7); d[0] = v[0]; d[1] = v[1]; d[2] = v[2]; d[3] = v[3]; }
;     asm volatile("s_waitcnt lgkmcnt(0)" ::: "memory");
;     const int c = lane & 7;
; #pragma unroll
;     for (int j = 0; j < 4; ++j) { const int n = (lane >> 3) + 8 * j; const LAS float* s = scr + (8 * c) * 33 + n;
;         u32x4 o; o.x = pk2(s[0 * 33], s[1 * 33]); o.y = pk2(s[2 * 33], s[3 * 33]); o.z = pk2(s[4 * 33], s[5 * 33]); o.w = pk2(s[6 * 33], s[7 * 33]);
;         *(u32x4*)(WT + (size_t)(dstrow + n) * K + k0 + 8 * c) = o; }
;     asm volatile("s_waitcnt lgkmcnt(0)" ::: "memory");
; }
; __device__ __forceinline__ void conv_item(const Params& P, int l, int r, LAS float* scr, int lane) {
;     ...
;     { const int kb = r / 32, gd = r % 32; transpose_item(P.w_ffn_out + (size_t)l * DFF * DM, DM, 32 * gd, nullptr, Wf2_ + (size_t)l * DM * DFF, DFF, 32 * gd, 64 * kb, scr, lane); }
	s_lshl_b32 s0, s15, 5
	s_and_b32 s8, s0, 0x3e0
	s_lshl_b32 s0, s15, 1
	s_and_b32 s0, s0, 0x7fffffc0
	s_addk_i32 s0, 0xdd00
	v_or_b32_e32 v40, s0, v39
	s_lshl_b32 s10, s8, 2
	v_or_b32_e32 v4, 8, v40
	v_mov_b32_e32 v5, v41
	v_or_b32_e32 v10, 16, v40
	v_mov_b32_e32 v11, v41
	v_or_b32_e32 v12, 24, v40
	v_mov_b32_e32 v13, v41
	v_or_b32_e32 v18, 32, v40
	v_mov_b32_e32 v19, v41
	v_or_b32_e32 v20, 40, v40
	v_mov_b32_e32 v21, v41
	v_lshl_add_u64 v[30:31], v[42:43], 0, s[10:11]
	v_lshlrev_b64 v[2:3], 12, v[40:41]
	v_lshlrev_b64 v[4:5], 12, v[4:5]
	v_lshlrev_b64 v[10:11], 12, v[10:11]
	v_lshlrev_b64 v[12:13], 12, v[12:13]
	v_lshlrev_b64 v[18:19], 12, v[18:19]
	v_lshlrev_b64 v[20:21], 12, v[20:21]
	v_lshl_add_u64 v[2:3], v[30:31], 0, v[2:3]
	v_lshl_add_u64 v[6:7], v[30:31], 0, v[4:5]
	v_lshl_add_u64 v[10:11], v[30:31], 0, v[10:11]
	v_lshl_add_u64 v[14:15], v[30:31], 0, v[12:13]
	v_lshl_add_u64 v[18:19], v[30:31], 0, v[18:19]
	v_lshl_add_u64 v[22:23], v[30:31], 0, v[20:21]
	global_load_dwordx4 v[2:5], v[2:3], off nt
	s_nop 0
	global_load_dwordx4 v[6:9], v[6:7], off nt
	s_nop 0
	global_load_dwordx4 v[10:13], v[10:11], off nt
	s_nop 0
	global_load_dwordx4 v[14:17], v[14:15], off nt
	s_nop 0
	global_load_dwordx4 v[18:21], v[18:19], off nt
	s_nop 0
	global_load_dwordx4 v[22:25], v[22:23], off nt
	v_or_b32_e32 v26, 48, v40
	v_mov_b32_e32 v27, v41
	v_lshlrev_b64 v[26:27], 12, v[26:27]
	v_lshl_add_u64 v[26:27], v[30:31], 0, v[26:27]
	v_or_b32_e32 v40, 56, v40
	global_load_dwordx4 v[26:29], v[26:27], off nt
	v_lshlrev_b64 v[32:33], 12, v[40:41]
	v_lshl_add_u64 v[30:31], v[30:31], 0, v[32:33]
	global_load_dwordx4 v[30:33], v[30:31], off nt
	v_or_b32_e32 v36, s8, v39
	s_mov_b32 s1, s11
	v_mul_u32_u24_e32 v36, 0xb00, v36
	v_lshl_add_u64 v[34:35], s[0:1], 1, v[44:45]
	v_lshlrev_b32_e32 v40, 1, v36
	s_mov_b64 s[0:1], 0
	s_waitcnt vmcnt(0)
	ds_write2_b32 v73, v2, v3 offset1:1
	ds_write2_b32 v73, v4, v5 offset0:2 offset1:3
	ds_write2_b32 v74, v6, v7 offset1:1
	ds_write2_b32 v75, v8, v9 offset1:1
	ds_write2_b32 v76, v10, v11 offset1:1
	ds_write2_b32 v77, v12, v13 offset1:1
	ds_write2_b32 v78, v14, v15 offset1:1
	ds_write2_b32 v79, v16, v17 offset1:1
	ds_write2_b32 v80, v18, v19 offset1:1
	ds_write2_b32 v81, v20, v21 offset1:1
	ds_write2_b32 v82, v22, v23 offset1:1
	ds_write2_b32 v83, v24, v25 offset1:1
	ds_write2_b32 v84, v26, v27 offset1:1
	ds_write2_b32 v85, v28, v29 offset1:1
	ds_write2_b32 v86, v30, v31 offset1:1
	ds_write2_b32 v87, v32, v33 offset1:1
	s_waitcnt lgkmcnt(0)
	ds_read2_b32 v[6:7], v68 offset0:33 offset1:41
	ds_read2_b32 v[8:9], v68 offset1:8
	ds_read2_b32 v[10:11], v68 offset0:66 offset1:74
	ds_read2_b32 v[12:13], v68 offset0:99 offset1:107
	ds_read2_b32 v[14:15], v68 offset0:132 offset1:140
	ds_read2_b32 v[16:17], v68 offset0:165 offset1:173
	ds_read2_b32 v[18:19], v68 offset0:198 offset1:206
	ds_read2_b32 v[20:21], v68 offset0:231 offset1:239
	s_waitcnt lgkmcnt(6)
	v_bfe_u32 v2, v8, 16, 1
	v_bfe_u32 v3, v6, 16, 1
	s_waitcnt lgkmcnt(5)
	v_bfe_u32 v4, v10, 16, 1
	s_waitcnt lgkmcnt(3)
	v_bfe_u32 v22, v14, 16, 1
	s_waitcnt lgkmcnt(1)
	v_bfe_u32 v24, v18, 16, 1
	v_bfe_u32 v5, v12, 16, 1
	v_bfe_u32 v23, v16, 16, 1
	s_waitcnt lgkmcnt(0)
	v_bfe_u32 v25, v20, 16, 1
	v_add3_u32 v2, v8, v2, s23
	v_add3_u32 v3, v6, v3, s23
	v_add3_u32 v4, v10, v4, s23
	v_add3_u32 v6, v14, v22, s23
	v_add3_u32 v10, v18, v24, s23
	v_add3_u32 v5, v12, v5, s23
	v_add3_u32 v8, v16, v23, s23
	v_add3_u32 v12, v20, v25, s23
	v_lshrrev_b32_e32 v2, 16, v2
	v_lshrrev_b32_e32 v4, 16, v4
	v_lshrrev_b32_e32 v6, 16, v6
	v_lshrrev_b32_e32 v10, 16, v10
	v_and_or_b32 v2, v3, s24, v2
	v_and_or_b32 v3, v5, s24, v4
	v_and_or_b32 v4, v8, s24, v6
	v_and_or_b32 v5, v12, s24, v10
	v_lshl_add_u64 v[22:23], v[34:35], 0, v[40:41]
	global_store_dwordx4 v[22:23], v[2:5], off
	v_bfe_u32 v6, v21, 16, 1
	v_add3_u32 v6, v21, v6, s23
	v_bfe_u32 v2, v9, 16, 1
	v_add3_u32 v2, v9, v2, s23
	v_bfe_u32 v3, v7, 16, 1
	v_lshrrev_b32_e32 v2, 16, v2
	v_add3_u32 v3, v7, v3, s23
	v_and_or_b32 v2, v3, s24, v2
	v_bfe_u32 v3, v11, 16, 1
	v_add3_u32 v3, v11, v3, s23
	v_bfe_u32 v4, v13, 16, 1
	v_lshrrev_b32_e32 v3, 16, v3
	v_add3_u32 v4, v13, v4, s23
	v_and_or_b32 v3, v4, s24, v3
	v_bfe_u32 v4, v15, 16, 1
	v_add3_u32 v4, v15, v4, s23
	v_bfe_u32 v5, v17, 16, 1
	v_lshrrev_b32_e32 v4, 16, v4
	v_add3_u32 v5, v17, v5, s23
	v_and_or_b32 v4, v5, s24, v4
	v_bfe_u32 v5, v19, 16, 1
	v_add3_u32 v5, v19, v5, s23
	v_lshrrev_b32_e32 v5, 16, v5
	v_and_or_b32 v5, v6, s24, v5
	v_or_b32_e32 v6, s8, v59
	v_mul_u32_u24_e32 v8, 0xb00, v6
	v_lshlrev_b32_e32 v40, 1, v8
	ds_read2_b32 v[6:7], v68 offset0:16 offset1:24
	v_lshl_add_u64 v[8:9], v[34:35], 0, v[40:41]
	global_store_dwordx4 v[8:9], v[2:5], off
	ds_read2_b32 v[8:9], v68 offset0:49 offset1:57
	ds_read2_b32 v[10:11], v68 offset0:82 offset1:90
	ds_read2_b32 v[12:13], v68 offset0:115 offset1:123
	s_waitcnt lgkmcnt(3)
	v_bfe_u32 v2, v6, 16, 1
	v_add3_u32 v2, v6, v2, s23
	s_waitcnt lgkmcnt(2)
	v_bfe_u32 v3, v8, 16, 1
	ds_read2_b32 v[14:15], v68 offset0:148 offset1:156
	v_lshrrev_b32_e32 v2, 16, v2
	v_add3_u32 v3, v8, v3, s23
	ds_read2_b32 v[16:17], v68 offset0:181 offset1:189
	v_and_or_b32 v2, v3, s24, v2
	s_waitcnt lgkmcnt(3)
	v_bfe_u32 v3, v10, 16, 1
	v_add3_u32 v3, v10, v3, s23
	s_waitcnt lgkmcnt(2)
	v_bfe_u32 v4, v12, 16, 1
	ds_read2_b32 v[18:19], v68 offset0:214 offset1:222
	v_lshrrev_b32_e32 v3, 16, v3
	v_add3_u32 v4, v12, v4, s23
	ds_read2_b32 v[20:21], v68 offset0:247 offset1:255
	v_and_or_b32 v3, v4, s24, v3
	s_waitcnt lgkmcnt(3)
	v_bfe_u32 v4, v14, 16, 1
	v_add3_u32 v4, v14, v4, s23
	s_waitcnt lgkmcnt(2)
	v_bfe_u32 v5, v16, 16, 1
	v_lshrrev_b32_e32 v4, 16, v4
	v_add3_u32 v5, v16, v5, s23
	v_and_or_b32 v4, v5, s24, v4
	s_waitcnt lgkmcnt(1)
	v_bfe_u32 v5, v18, 16, 1
	v_add3_u32 v5, v18, v5, s23
	s_waitcnt lgkmcnt(0)
	v_bfe_u32 v6, v20, 16, 1
	v_lshrrev_b32_e32 v5, 16, v5
	v_add3_u32 v6, v20, v6, s23
	v_and_or_b32 v5, v6, s24, v5
	v_or_b32_e32 v6, s8, v66
	v_mul_u32_u24_e32 v6, 0xb00, v6
	v_lshlrev_b32_e32 v40, 1, v6
	v_lshl_add_u64 v[22:23], v[34:35], 0, v[40:41]
	global_store_dwordx4 v[22:23], v[2:5], off
	v_bfe_u32 v6, v21, 16, 1
	v_add3_u32 v6, v21, v6, s23
	v_bfe_u32 v2, v7, 16, 1
	v_add3_u32 v2, v7, v2, s23
	v_bfe_u32 v3, v9, 16, 1
	v_lshrrev_b32_e32 v2, 16, v2
	v_add3_u32 v3, v9, v3, s23
	v_and_or_b32 v2, v3, s24, v2
	v_bfe_u32 v3, v11, 16, 1
	v_add3_u32 v3, v11, v3, s23
	v_bfe_u32 v4, v13, 16, 1
	v_lshrrev_b32_e32 v3, 16, v3
	v_add3_u32 v4, v13, v4, s23
	v_and_or_b32 v3, v4, s24, v3
	v_bfe_u32 v4, v15, 16, 1
	v_add3_u32 v4, v15, v4, s23
	v_bfe_u32 v5, v17, 16, 1
	v_lshrrev_b32_e32 v4, 16, v4
	v_add3_u32 v5, v17, v5, s23
	v_and_or_b32 v4, v5, s24, v4
	v_bfe_u32 v5, v19, 16, 1
	v_add3_u32 v5, v19, v5, s23
	v_lshrrev_b32_e32 v5, 16, v5
	v_and_or_b32 v5, v6, s24, v5
	v_or_b32_e32 v6, s8, v67
	v_mul_u32_u24_e32 v6, 0xb00, v6
	v_lshlrev_b32_e32 v40, 1, v6
	v_lshl_add_u64 v[6:7], v[34:35], 0, v[40:41]
	global_store_dwordx4 v[6:7], v[2:5], off
	s_waitcnt lgkmcnt(0)
